# out-proj light tile epilogue: the 7 later residual elements are requested together with the first (they were load-wait-store one at a time)
# baseline (speedup 1.0000x reference)
; #define LAS __attribute__((address_space(3)))
; template <int MODE> DEVI void light_gemm_tile(const bf16_t* A, const bf16_t* Bt, int row0, int col0, bf16_t* Obf, int ldo, float* X, const float* Xin, const float* gate, LAS unsigned char* lds, int tid, int wave, int lane) {
;     const int r32 = lane & 31, h = lane >> 5;
;     bf16x8_t af[2][8], bfr[2][8];
; #pragma unroll
;     for (int rb = 0; rb < 2; ++rb)
; #pragma unroll
;         for (int ks = 0; ks < 8; ++ks) {
;             af[rb][ks] = *(const bf16x8_t*)(A + (size_t)(row0 + 32 * rb + r32) * D + 128 * wave + 16 * ks + 8 * h);
;             bfr[rb][ks] = *(const bf16x8_t*)(Bt + (size_t)(col0 + 32 * rb + r32) * D + 128 * wave + 16 * ks + 8 * h);
;         }
;     LAS float* part = (LAS float*)lds;
; #pragma unroll
;     for (int rb = 0; rb < 2; ++rb)
; #pragma unroll
;         for (int cb = 0; cb < 2; ++cb) {
;             f32x16_t acc = {0.f, 0.f, 0.f, 0.f, 0.f, 0.f, 0.f, 0.f, 0.f, 0.f, 0.f, 0.f, 0.f, 0.f, 0.f, 0.f};
; #pragma unroll
;             for (int ks = 0; ks < 8; ++ks) acc = __builtin_amdgcn_mfma_f32_32x32x16_bf16(af[rb][ks], bfr[cb][ks], acc, 0, 0, 0);
; #pragma unroll
;             for (int g = 0; g < 16; ++g) part[((wave * 4 + rb * 2 + cb) * 16 + g) * 64 + lane] = acc[g];
;         }
;     __syncthreads();
; #pragma unroll
;     for (int i = 0; i < 8; ++i) {
;         const int o = tid + 512 * i; const int ln = o & 63, g = (o >> 6) & 15, t4 = o >> 10;
;         float v = 0.f;
; #pragma unroll
;         for (int w = 0; w < 8; ++w) v += part[((w * 4 + t4) * 16 + g) * 64 + ln];
;         const int row = row0 + 32 * (t4 >> 1) + (g & 3) + 8 * (g >> 2) + 4 * (ln >> 5), col = col0 + 32 * (t4 & 1) + (ln & 31);
.LBB0_802:
	s_ashr_i32 s8, s10, 31
	s_lshr_b32 s8, s8, 28
	s_add_i32 s8, s10, s8
	s_ashr_i32 s9, s8, 4
	s_lshl_b32 s8, s9, 6
	s_addk_i32 s8, 0x4000
	v_or_b32_e32 v2, s8, v1
	v_ashrrev_i32_e32 v3, 31, v2
	s_lshl_b32 s11, s9, 10
	v_lshlrev_b64 v[6:7], 11, v[2:3]
	v_subrev_u32_e32 v4, s11, v101
	v_lshl_add_u64 v[174:175], v[70:71], 0, v[6:7]
	v_subrev_u32_e32 v74, 32, v4
	global_load_dwordx4 v[18:21], v[174:175], off
	v_ashrrev_i32_e32 v75, 31, v74
	v_ashrrev_i32_e32 v5, 31, v4
	v_lshlrev_b64 v[6:7], 11, v[74:75]
	v_lshlrev_b64 v[4:5], 11, v[4:5]
	v_lshl_add_u64 v[200:201], v[72:73], 0, v[6:7]
	v_lshl_add_u64 v[202:203], v[72:73], 0, v[4:5]
	global_load_dwordx4 v[34:37], v[200:201], off
	global_load_dwordx4 v[50:53], v[202:203], off
	v_or_b32_e32 v2, 32, v2
	v_ashrrev_i32_e32 v3, 31, v2
	v_lshlrev_b64 v[2:3], 11, v[2:3]
	v_lshl_add_u64 v[220:221], v[70:71], 0, v[2:3]
	global_load_dwordx4 v[54:57], v[174:175], off offset:32
	global_load_dwordx4 v[58:61], v[200:201], off offset:32
	global_load_dwordx4 v[62:65], v[220:221], off
	global_load_dwordx4 v[142:145], v[202:203], off offset:32
	global_load_dwordx4 v[146:149], v[220:221], off offset:32
	global_load_dwordx4 v[150:153], v[174:175], off offset:64
	global_load_dwordx4 v[154:157], v[200:201], off offset:64
	s_waitcnt vmcnt(0)
	v_mfma_f32_32x32x16_bf16 v[2:17], v[18:21], v[34:37], 0
	v_mfma_f32_32x32x16_bf16 v[18:33], v[18:21], v[50:53], 0
	v_mfma_f32_32x32x16_bf16 v[2:17], v[54:57], v[58:61], v[2:17]
	v_mfma_f32_32x32x16_bf16 v[18:33], v[54:57], v[142:145], v[18:33]
	global_load_dwordx4 v[158:161], v[202:203], off offset:64
	global_load_dwordx4 v[54:57], v[174:175], off offset:96
	v_mfma_f32_32x32x16_bf16 v[34:49], v[62:65], v[34:37], 0
	v_mfma_f32_32x32x16_bf16 v[34:49], v[146:149], v[58:61], v[34:49]
	global_load_dwordx4 v[58:61], v[200:201], off offset:96
	global_load_dwordx4 v[162:165], v[202:203], off offset:96
	global_load_dwordx4 v[166:169], v[174:175], off offset:128
	v_mfma_f32_32x32x16_bf16 v[2:17], v[150:153], v[154:157], v[2:17]
	s_waitcnt vmcnt(4)
	v_mfma_f32_32x32x16_bf16 v[18:33], v[150:153], v[158:161], v[18:33]
	global_load_dwordx4 v[150:153], v[200:201], off offset:128
	global_load_dwordx4 v[170:173], v[202:203], off offset:128
	global_load_dwordx4 v[180:183], v[174:175], off offset:160
	s_waitcnt vmcnt(5)
	v_mfma_f32_32x32x16_bf16 v[2:17], v[54:57], v[58:61], v[2:17]
	s_waitcnt vmcnt(4)
	v_mfma_f32_32x32x16_bf16 v[18:33], v[54:57], v[162:165], v[18:33]
	global_load_dwordx4 v[54:57], v[200:201], off offset:160
	global_load_dwordx4 v[184:187], v[202:203], off offset:160
	global_load_dwordx4 v[188:191], v[174:175], off offset:192
	s_waitcnt vmcnt(4)
	v_mfma_f32_32x32x16_bf16 v[18:33], v[166:169], v[170:173], v[18:33]
	v_mfma_f32_32x32x16_bf16 v[2:17], v[166:169], v[150:153], v[2:17]
	global_load_dwordx4 v[166:169], v[200:201], off offset:192
	global_load_dwordx4 v[192:195], v[202:203], off offset:192
	global_load_dwordx4 v[196:199], v[174:175], off offset:224
	global_load_dwordx4 v[216:219], v[220:221], off offset:160
	s_waitcnt vmcnt(6)
	v_mfma_f32_32x32x16_bf16 v[2:17], v[180:183], v[54:57], v[2:17]
	s_waitcnt vmcnt(5)
	v_mfma_f32_32x32x16_bf16 v[18:33], v[180:183], v[184:187], v[18:33]
	global_load_dwordx4 v[180:183], v[200:201], off offset:224
	s_waitcnt vmcnt(4)
	v_mfma_f32_32x32x16_bf16 v[2:17], v[188:191], v[166:169], v[2:17]
	s_waitcnt vmcnt(3)
	v_mfma_f32_32x32x16_bf16 v[18:33], v[188:191], v[192:195], v[18:33]
	global_load_dwordx4 v[188:191], v[220:221], off offset:64
	s_nop 0
	global_load_dwordx4 v[200:203], v[202:203], off offset:224
	s_waitcnt vmcnt(2)
	v_mfma_f32_32x32x16_bf16 v[2:17], v[196:199], v[180:183], v[2:17]
	s_waitcnt vmcnt(1)
	v_mfma_f32_32x32x16_bf16 v[34:49], v[188:191], v[154:157], v[34:49]
	global_load_dwordx4 v[154:157], v[220:221], off offset:128
	s_waitcnt vmcnt(1)
	v_mfma_f32_32x32x16_bf16 v[18:33], v[196:199], v[200:203], v[18:33]
	global_load_dwordx4 v[196:199], v[220:221], off offset:96
	s_waitcnt vmcnt(0)
	v_mfma_f32_32x32x16_bf16 v[34:49], v[196:199], v[58:61], v[34:49]
	v_mfma_f32_32x32x16_bf16 v[34:49], v[154:157], v[150:153], v[34:49]
	global_load_dwordx4 v[150:153], v[220:221], off offset:192
	s_nop 0
	global_load_dwordx4 v[220:223], v[220:221], off offset:224
	ds_write2st64_b32 v66, v2, v3 offset1:1
	ds_write2st64_b32 v66, v4, v5 offset0:2 offset1:3
	ds_write2st64_b32 v66, v6, v7 offset0:4 offset1:5
	ds_write2st64_b32 v66, v8, v9 offset0:6 offset1:7
	ds_write2st64_b32 v66, v10, v11 offset0:8 offset1:9
	ds_write2st64_b32 v66, v12, v13 offset0:10 offset1:11
	ds_write2st64_b32 v66, v14, v15 offset0:12 offset1:13
	ds_write2st64_b32 v66, v16, v17 offset0:14 offset1:15
	ds_write2st64_b32 v66, v18, v19 offset0:16 offset1:17
	ds_write2st64_b32 v66, v20, v21 offset0:18 offset1:19
	v_or_b32_e32 v12, s8, v76
	v_add_u32_e32 v19, v12, v77
	v_mfma_f32_32x32x16_bf16 v[34:49], v[216:219], v[54:57], v[34:49]
	v_or_b32_e32 v10, v78, v19
	v_add_u32_e32 v6, v74, v79
	v_ashrrev_i32_e32 v11, 31, v10
	v_lshlrev_b64 v[2:3], 10, v[10:11]
	v_ashrrev_i32_e32 v7, 31, v6
	v_lshl_add_u64 v[8:9], v[2:3], 0, v[6:7]
	v_lshl_add_u64 v[2:3], v[8:9], 2, s[6:7]
	v_mfma_f32_32x32x16_bf16 v[50:65], v[62:65], v[50:53], 0
	v_cmp_lt_i32_e32 vcc, s62, v10
	v_mfma_f32_32x32x16_bf16 v[50:65], v[146:149], v[142:145], v[50:65]
	v_mfma_f32_32x32x16_bf16 v[50:65], v[188:191], v[158:161], v[50:65]
	v_mfma_f32_32x32x16_bf16 v[50:65], v[196:199], v[162:165], v[50:65]
	v_mfma_f32_32x32x16_bf16 v[50:65], v[154:157], v[170:173], v[50:65]
	v_mfma_f32_32x32x16_bf16 v[50:65], v[216:219], v[184:187], v[50:65]
	s_waitcnt vmcnt(1)
; DEVI bf16_t f2bf(float f) { unsigned u = __float_as_uint(f); return (bf16_t)((u + 0x7fffu + ((u >> 16) & 1u)) >> 16); }
; template <int MODE> DEVI void light_gemm_tile(const bf16_t* A, const bf16_t* Bt, int row0, int col0, bf16_t* Obf, int ldo, float* X, const float* Xin, const float* gate, LAS unsigned char* lds, int tid, int wave, int lane) {
;     ...
;             for (int ks = 0; ks < 8; ++ks) acc = __builtin_amdgcn_mfma_f32_32x32x16_bf16(af[rb][ks], bfr[cb][ks], acc, 0, 0, 0);
; #pragma unroll
;             for (int g = 0; g < 16; ++g) part[((wave * 4 + rb * 2 + cb) * 16 + g) * 64 + lane] = acc[g];
;         }
;     __syncthreads();
; #pragma unroll
;     for (int i = 0; i < 8; ++i) {
;         const int o = tid + 512 * i; const int ln = o & 63, g = (o >> 6) & 15, t4 = o >> 10;
;         float v = 0.f;
; #pragma unroll
;         for (int w = 0; w < 8; ++w) v += part[((w * 4 + t4) * 16 + g) * 64 + ln];
;         const int row = row0 + 32 * (t4 >> 1) + (g & 3) + 8 * (g >> 2) + 4 * (ln >> 5), col = col0 + 32 * (t4 & 1) + (ln & 31);
;         if (MODE == 0) Obf[(size_t)row * ldo + col] = f2bf(v);
;         else X[(size_t)row * D + col] = Xin[(size_t)row * D + col] + gate[(size_t)row_seq(row) * 6144 + col] * v;
;     }
	v_mfma_f32_32x32x16_bf16 v[34:49], v[150:153], v[166:169], v[34:49]
	v_mfma_f32_32x32x16_bf16 v[50:65], v[150:153], v[192:195], v[50:65]
	s_waitcnt vmcnt(0)
	v_mfma_f32_32x32x16_bf16 v[34:49], v[220:223], v[180:183], v[34:49]
	ds_write2st64_b32 v66, v22, v23 offset0:20 offset1:21
	ds_write2st64_b32 v66, v24, v25 offset0:22 offset1:23
	ds_write2st64_b32 v66, v26, v27 offset0:24 offset1:25
	ds_write2st64_b32 v66, v28, v29 offset0:26 offset1:27
	ds_write2st64_b32 v66, v30, v31 offset0:28 offset1:29
	ds_write2st64_b32 v66, v32, v33 offset0:30 offset1:31
	s_nop 5
	ds_write2st64_b32 v66, v34, v35 offset0:32 offset1:33
	ds_write2st64_b32 v66, v36, v37 offset0:34 offset1:35
	ds_write2st64_b32 v66, v38, v39 offset0:36 offset1:37
	ds_write2st64_b32 v66, v40, v41 offset0:38 offset1:39
	ds_write2st64_b32 v66, v42, v43 offset0:40 offset1:41
	ds_write2st64_b32 v66, v44, v45 offset0:42 offset1:43
	ds_write2st64_b32 v66, v46, v47 offset0:44 offset1:45
	ds_write2st64_b32 v66, v48, v49 offset0:46 offset1:47
	v_mfma_f32_32x32x16_bf16 v[50:65], v[220:223], v[200:203], v[50:65]
	s_nop 11
	ds_write2st64_b32 v66, v50, v51 offset0:48 offset1:49
	ds_write2st64_b32 v66, v52, v53 offset0:50 offset1:51
	ds_write2st64_b32 v66, v54, v55 offset0:52 offset1:53
	ds_write2st64_b32 v66, v56, v57 offset0:54 offset1:55
	ds_write2st64_b32 v66, v58, v59 offset0:56 offset1:57
	ds_write2st64_b32 v66, v60, v61 offset0:58 offset1:59
	ds_write2st64_b32 v66, v62, v63 offset0:60 offset1:61
	ds_write2st64_b32 v66, v64, v65 offset0:62 offset1:63
	s_waitcnt lgkmcnt(0)
	s_barrier
	global_load_dword v13, v[2:3], off
	s_mov_b32 s9, 0
	s_mov_b32 s8, 0x10000
	v_lshl_add_u64 v[150:151], v[2:3], 0, s[8:9]
	global_load_dword v152, v[150:151], off
	global_load_dword v152, v[2:3], off offset:128
	global_load_dword v152, v[150:151], off offset:128
	s_mov_b32 s8, 0x20000
	v_lshl_add_u64 v[150:151], v[2:3], 0, s[8:9]
	global_load_dword v152, v[150:151], off
	global_load_dword v152, v[150:151], off offset:128
	s_mov_b32 s8, 0x30000
	v_lshl_add_u64 v[150:151], v[2:3], 0, s[8:9]
	global_load_dword v152, v[150:151], off
	global_load_dword v152, v[150:151], off offset:128
	ds_read2st64_b32 v[4:5], v102 offset1:64
	ds_read2st64_b32 v[2:3], v102 offset0:128 offset1:192
	ds_read_b32 v17, v103
	ds_read_b32 v14, v104
	ds_read_b32 v15, v105
	ds_read_b32 v16, v106
	s_and_saveexec_b64 s[8:9], vcc
	s_xor_b64 s[8:9], exec, s[8:9]
	v_add_u32_e32 v10, 0xffffc000, v19
	v_lshrrev_b32_e32 v10, 6, v10
	v_add_u32_e32 v18, 2, v10
	s_andn2_saveexec_b64 s[8:9], s[8:9]
	v_lshrrev_b32_e32 v11, 19, v11
	v_add_u32_e32 v10, v10, v11
	v_ashrrev_i32_e32 v18, 13, v10
	s_or_b64 exec, exec, s[8:9]
	s_movk_i32 s8, 0x6000
	v_mad_i64_i32 v[10:11], s[8:9], v18, s8, v[68:69]
	v_lshl_add_u64 v[6:7], v[6:7], 2, v[10:11]
	global_load_dword v19, v[6:7], off
	s_waitcnt lgkmcnt(5)
	v_add_f32_e32 v4, 0, v4
	s_sub_i32 s11, 0, s11
	v_add_u32_e32 v18, v12, v80
	v_add_f32_e32 v4, v4, v5
	v_or_b32_e32 v10, v81, v18
	v_add3_u32 v5, v82, v101, s11
	s_waitcnt lgkmcnt(4)
	v_add_f32_e32 v2, v4, v2
	v_lshl_add_u64 v[6:7], v[8:9], 2, s[2:3]
	v_subrev_u32_e32 v4, 32, v5
	v_ashrrev_i32_e32 v11, 31, v10
	v_add_f32_e32 v8, v2, v3
	v_lshlrev_b64 v[2:3], 10, v[10:11]
	v_ashrrev_i32_e32 v5, 31, v4
	s_waitcnt lgkmcnt(3)
	v_add_f32_e32 v17, v8, v17
	v_lshl_add_u64 v[8:9], v[2:3], 0, v[4:5]
	s_waitcnt lgkmcnt(2)
	v_add_f32_e32 v2, v17, v14
	s_waitcnt lgkmcnt(1)
	v_add_f32_e32 v2, v2, v15
	s_waitcnt lgkmcnt(0)
	v_add_f32_e32 v2, v2, v16
	v_cmp_lt_i32_e32 vcc, s62, v10
	s_waitcnt vmcnt(0)
	v_fmac_f32_e32 v13, v2, v19
	global_store_dword v[6:7], v13, off
	v_lshl_add_u64 v[2:3], v[8:9], 2, s[6:7]
	global_load_dword v13, v[2:3], off
	ds_read2st64_b32 v[6:7], v107 offset1:64
	ds_read2st64_b32 v[2:3], v107 offset0:128 offset1:192
	ds_read_b32 v17, v108
	ds_read_b32 v14, v109
	ds_read_b32 v15, v110
	ds_read_b32 v16, v111
	s_and_saveexec_b64 s[8:9], vcc
	s_xor_b64 s[8:9], exec, s[8:9]
	v_add_u32_e32 v10, 0xffffc000, v18
	v_lshrrev_b32_e32 v10, 6, v10
	v_add_u32_e32 v19, 2, v10
	s_andn2_saveexec_b64 s[8:9], s[8:9]
	v_lshrrev_b32_e32 v11, 19, v11
	v_add_u32_e32 v10, v10, v11
	v_ashrrev_i32_e32 v19, 13, v10
	s_or_b64 exec, exec, s[8:9]
	s_movk_i32 s8, 0x6000
	v_mad_i64_i32 v[10:11], s[8:9], v19, s8, v[68:69]
	v_lshl_add_u64 v[4:5], v[4:5], 2, v[10:11]
	global_load_dword v19, v[4:5], off
	s_waitcnt lgkmcnt(5)
	v_add_f32_e32 v4, 0, v6
	v_add_u32_e32 v18, v12, v83
	v_add_f32_e32 v6, v4, v7
	v_add3_u32 v5, v85, v101, s11
	v_or_b32_e32 v10, v84, v18
	s_waitcnt lgkmcnt(4)
	v_add_f32_e32 v2, v6, v2
	v_subrev_u32_e32 v4, 32, v5
	v_ashrrev_i32_e32 v11, 31, v10
	v_add_f32_e32 v6, v2, v3
	v_ashrrev_i32_e32 v5, 31, v4
	v_lshlrev_b64 v[2:3], 10, v[10:11]
	s_waitcnt lgkmcnt(3)
	v_add_f32_e32 v6, v6, v17
	v_lshl_add_u64 v[20:21], v[8:9], 2, s[2:3]
	v_lshl_add_u64 v[8:9], v[2:3], 0, v[4:5]
	s_waitcnt lgkmcnt(2)
	v_add_f32_e32 v2, v6, v14
	s_waitcnt lgkmcnt(1)
	v_add_f32_e32 v2, v2, v15
	s_waitcnt lgkmcnt(0)
	v_add_f32_e32 v2, v2, v16
	v_cmp_lt_i32_e32 vcc, s62, v10
	s_waitcnt vmcnt(0)
	v_fmac_f32_e32 v13, v2, v19
	global_store_dword v[20:21], v13, off
	v_lshl_add_u64 v[2:3], v[8:9], 2, s[6:7]
	global_load_dword v13, v[2:3], off
	ds_read2st64_b32 v[6:7], v112 offset1:64
	ds_read2st64_b32 v[2:3], v112 offset0:128 offset1:192
	ds_read_b32 v17, v113
	ds_read_b32 v14, v114
	ds_read_b32 v15, v115
	ds_read_b32 v16, v116
	s_and_saveexec_b64 s[8:9], vcc
	s_xor_b64 s[8:9], exec, s[8:9]
	v_add_u32_e32 v10, 0xffffc000, v18
	v_lshrrev_b32_e32 v10, 6, v10
	v_add_u32_e32 v19, 2, v10
	s_andn2_saveexec_b64 s[8:9], s[8:9]
	v_lshrrev_b32_e32 v11, 19, v11
	v_add_u32_e32 v10, v10, v11
	v_ashrrev_i32_e32 v19, 13, v10
	s_or_b64 exec, exec, s[8:9]
	s_movk_i32 s8, 0x6000
	v_mad_i64_i32 v[10:11], s[8:9], v19, s8, v[68:69]
	v_lshl_add_u64 v[4:5], v[4:5], 2, v[10:11]
	global_load_dword v19, v[4:5], off
	s_waitcnt lgkmcnt(5)
; DEVI bf16_t f2bf(float f) { unsigned u = __float_as_uint(f); return (bf16_t)((u + 0x7fffu + ((u >> 16) & 1u)) >> 16); }
; template <int MODE> DEVI void light_gemm_tile(const bf16_t* A, const bf16_t* Bt, int row0, int col0, bf16_t* Obf, int ldo, float* X, const float* Xin, const float* gate, LAS unsigned char* lds, int tid, int wave, int lane) {
;     ...
;     for (int i = 0; i < 8; ++i) {
;         const int o = tid + 512 * i; const int ln = o & 63, g = (o >> 6) & 15, t4 = o >> 10;
;         float v = 0.f;
; #pragma unroll
;         for (int w = 0; w < 8; ++w) v += part[((w * 4 + t4) * 16 + g) * 64 + ln];
;         const int row = row0 + 32 * (t4 >> 1) + (g & 3) + 8 * (g >> 2) + 4 * (ln >> 5), col = col0 + 32 * (t4 & 1) + (ln & 31);
;         if (MODE == 0) Obf[(size_t)row * ldo + col] = f2bf(v);
;         else X[(size_t)row * D + col] = Xin[(size_t)row * D + col] + gate[(size_t)row_seq(row) * 6144 + col] * v;
	v_add_f32_e32 v4, 0, v6
	v_add_u32_e32 v18, v12, v86
	v_add_f32_e32 v6, v4, v7
	v_add3_u32 v5, v88, v101, s11
	v_or_b32_e32 v10, v87, v18
	s_waitcnt lgkmcnt(4)
	v_add_f32_e32 v2, v6, v2
	v_subrev_u32_e32 v4, 32, v5
	v_ashrrev_i32_e32 v11, 31, v10
	v_add_f32_e32 v6, v2, v3
	v_ashrrev_i32_e32 v5, 31, v4
	v_lshlrev_b64 v[2:3], 10, v[10:11]
	s_waitcnt lgkmcnt(3)
	v_add_f32_e32 v6, v6, v17
	v_lshl_add_u64 v[20:21], v[8:9], 2, s[2:3]
	v_lshl_add_u64 v[8:9], v[2:3], 0, v[4:5]
	s_waitcnt lgkmcnt(2)
	v_add_f32_e32 v2, v6, v14
	s_waitcnt lgkmcnt(1)
	v_add_f32_e32 v2, v2, v15
	s_waitcnt lgkmcnt(0)
	v_add_f32_e32 v2, v2, v16
	v_cmp_lt_i32_e32 vcc, s62, v10
	s_waitcnt vmcnt(0)
	v_fmac_f32_e32 v13, v2, v19
	global_store_dword v[20:21], v13, off
	v_lshl_add_u64 v[2:3], v[8:9], 2, s[6:7]
	global_load_dword v13, v[2:3], off
	ds_read2st64_b32 v[6:7], v117 offset1:64
	ds_read2st64_b32 v[2:3], v117 offset0:128 offset1:192
	ds_read_b32 v17, v118
	ds_read_b32 v14, v119
	ds_read_b32 v15, v120
	ds_read_b32 v16, v121
	s_and_saveexec_b64 s[8:9], vcc
	s_xor_b64 s[8:9], exec, s[8:9]
	v_add_u32_e32 v10, 0xffffc000, v18
	v_lshrrev_b32_e32 v10, 6, v10
	v_add_u32_e32 v19, 2, v10
	s_andn2_saveexec_b64 s[8:9], s[8:9]
	v_lshrrev_b32_e32 v11, 19, v11
	v_add_u32_e32 v10, v10, v11
	v_ashrrev_i32_e32 v19, 13, v10
	s_or_b64 exec, exec, s[8:9]
	s_movk_i32 s8, 0x6000
	v_mad_i64_i32 v[10:11], s[8:9], v19, s8, v[68:69]
	v_lshl_add_u64 v[4:5], v[4:5], 2, v[10:11]
	global_load_dword v19, v[4:5], off
	s_waitcnt lgkmcnt(5)
	v_add_f32_e32 v4, 0, v6
	v_add_u32_e32 v18, v12, v89
	v_add_f32_e32 v6, v4, v7
	v_add3_u32 v5, v91, v101, s11
	v_or_b32_e32 v10, v90, v18
	s_waitcnt lgkmcnt(4)
	v_add_f32_e32 v2, v6, v2
	v_subrev_u32_e32 v4, 32, v5
	v_ashrrev_i32_e32 v11, 31, v10
	v_add_f32_e32 v6, v2, v3
	v_ashrrev_i32_e32 v5, 31, v4
	v_lshlrev_b64 v[2:3], 10, v[10:11]
	s_waitcnt lgkmcnt(3)
	v_add_f32_e32 v6, v6, v17
	v_lshl_add_u64 v[20:21], v[8:9], 2, s[2:3]
	v_lshl_add_u64 v[8:9], v[2:3], 0, v[4:5]
	s_waitcnt lgkmcnt(2)
	v_add_f32_e32 v2, v6, v14
	s_waitcnt lgkmcnt(1)
	v_add_f32_e32 v2, v2, v15
	s_waitcnt lgkmcnt(0)
	v_add_f32_e32 v2, v2, v16
	v_cmp_lt_i32_e32 vcc, s62, v10
	s_waitcnt vmcnt(0)
	v_fmac_f32_e32 v13, v2, v19
	global_store_dword v[20:21], v13, off
	v_lshl_add_u64 v[2:3], v[8:9], 2, s[6:7]
	global_load_dword v13, v[2:3], off
	ds_read2st64_b32 v[6:7], v122 offset1:64
	ds_read2st64_b32 v[2:3], v122 offset0:128 offset1:192
	ds_read_b32 v17, v123
	ds_read_b32 v14, v124
	ds_read_b32 v15, v125
	ds_read_b32 v16, v126
	s_and_saveexec_b64 s[8:9], vcc
	s_xor_b64 s[8:9], exec, s[8:9]
	v_add_u32_e32 v10, 0xffffc000, v18
	v_lshrrev_b32_e32 v10, 6, v10
	v_add_u32_e32 v19, 2, v10
	s_andn2_saveexec_b64 s[8:9], s[8:9]
	v_lshrrev_b32_e32 v11, 19, v11
	v_add_u32_e32 v10, v10, v11
	v_ashrrev_i32_e32 v19, 13, v10
	s_or_b64 exec, exec, s[8:9]
	s_movk_i32 s8, 0x6000
	v_mad_i64_i32 v[10:11], s[8:9], v19, s8, v[68:69]
	v_lshl_add_u64 v[4:5], v[4:5], 2, v[10:11]
	global_load_dword v19, v[4:5], off
	s_waitcnt lgkmcnt(5)
	v_add_f32_e32 v4, 0, v6
	v_add_u32_e32 v18, v12, v92
	v_add_f32_e32 v6, v4, v7
	v_add3_u32 v5, v94, v101, s11
	v_or_b32_e32 v10, v93, v18
	s_waitcnt lgkmcnt(4)
	v_add_f32_e32 v2, v6, v2
	v_subrev_u32_e32 v4, 32, v5
	v_ashrrev_i32_e32 v11, 31, v10
	v_add_f32_e32 v6, v2, v3
	v_ashrrev_i32_e32 v5, 31, v4
	v_lshlrev_b64 v[2:3], 10, v[10:11]
	s_waitcnt lgkmcnt(3)
	v_add_f32_e32 v6, v6, v17
	v_lshl_add_u64 v[20:21], v[8:9], 2, s[2:3]
	v_lshl_add_u64 v[8:9], v[2:3], 0, v[4:5]
	s_waitcnt lgkmcnt(2)
	v_add_f32_e32 v2, v6, v14
	s_waitcnt lgkmcnt(1)
	v_add_f32_e32 v2, v2, v15
	s_waitcnt lgkmcnt(0)
	v_add_f32_e32 v2, v2, v16
	v_cmp_lt_i32_e32 vcc, s62, v10
	s_waitcnt vmcnt(0)
; DEVI bf16_t f2bf(float f) { unsigned u = __float_as_uint(f); return (bf16_t)((u + 0x7fffu + ((u >> 16) & 1u)) >> 16); }
; template <int MODE> DEVI void light_gemm_tile(const bf16_t* A, const bf16_t* Bt, int row0, int col0, bf16_t* Obf, int ldo, float* X, const float* Xin, const float* gate, LAS unsigned char* lds, int tid, int wave, int lane) {
;     ...
;     for (int i = 0; i < 8; ++i) {
;         const int o = tid + 512 * i; const int ln = o & 63, g = (o >> 6) & 15, t4 = o >> 10;
;         float v = 0.f;
; #pragma unroll
;         for (int w = 0; w < 8; ++w) v += part[((w * 4 + t4) * 16 + g) * 64 + ln];
;         const int row = row0 + 32 * (t4 >> 1) + (g & 3) + 8 * (g >> 2) + 4 * (ln >> 5), col = col0 + 32 * (t4 & 1) + (ln & 31);
;         if (MODE == 0) Obf[(size_t)row * ldo + col] = f2bf(v);
;         else X[(size_t)row * D + col] = Xin[(size_t)row * D + col] + gate[(size_t)row_seq(row) * 6144 + col] * v;
	v_fmac_f32_e32 v13, v2, v19
	global_store_dword v[20:21], v13, off
	v_lshl_add_u64 v[2:3], v[8:9], 2, s[6:7]
	global_load_dword v13, v[2:3], off
	ds_read2st64_b32 v[6:7], v127 offset1:64
	ds_read2st64_b32 v[2:3], v127 offset0:128 offset1:192
	ds_read_b32 v17, v128
	ds_read_b32 v14, v129
	ds_read_b32 v15, v130
	ds_read_b32 v16, v131
	s_and_saveexec_b64 s[8:9], vcc
	s_xor_b64 s[8:9], exec, s[8:9]
	v_add_u32_e32 v10, 0xffffc000, v18
	v_lshrrev_b32_e32 v10, 6, v10
	v_add_u32_e32 v19, 2, v10
	s_andn2_saveexec_b64 s[8:9], s[8:9]
	v_lshrrev_b32_e32 v11, 19, v11
	v_add_u32_e32 v10, v10, v11
	v_ashrrev_i32_e32 v19, 13, v10
	s_or_b64 exec, exec, s[8:9]
	s_movk_i32 s8, 0x6000
	v_mad_i64_i32 v[10:11], s[8:9], v19, s8, v[68:69]
	v_lshl_add_u64 v[4:5], v[4:5], 2, v[10:11]
	global_load_dword v19, v[4:5], off
	s_waitcnt lgkmcnt(5)
	v_add_f32_e32 v4, 0, v6
	v_add_u32_e32 v18, v12, v95
	v_add_f32_e32 v6, v4, v7
	v_add3_u32 v5, v97, v101, s11
	v_or_b32_e32 v10, v96, v18
	s_waitcnt lgkmcnt(4)
	v_add_f32_e32 v2, v6, v2
	v_subrev_u32_e32 v4, 32, v5
	v_ashrrev_i32_e32 v11, 31, v10
	v_add_f32_e32 v6, v2, v3
	v_ashrrev_i32_e32 v5, 31, v4
	v_lshlrev_b64 v[2:3], 10, v[10:11]
	s_waitcnt lgkmcnt(3)
	v_add_f32_e32 v6, v6, v17
	v_lshl_add_u64 v[20:21], v[8:9], 2, s[2:3]
	v_lshl_add_u64 v[8:9], v[2:3], 0, v[4:5]
	s_waitcnt lgkmcnt(2)
	v_add_f32_e32 v2, v6, v14
	s_waitcnt lgkmcnt(1)
	v_add_f32_e32 v2, v2, v15
	s_waitcnt lgkmcnt(0)
	v_add_f32_e32 v2, v2, v16
	v_cmp_lt_i32_e32 vcc, s62, v10
	s_waitcnt vmcnt(0)
	v_fmac_f32_e32 v13, v2, v19
	global_store_dword v[20:21], v13, off
	v_lshl_add_u64 v[2:3], v[8:9], 2, s[6:7]
	global_load_dword v13, v[2:3], off
	ds_read2st64_b32 v[6:7], v132 offset1:64
	ds_read2st64_b32 v[2:3], v132 offset0:128 offset1:192
	ds_read_b32 v17, v133
	ds_read_b32 v14, v134
	ds_read_b32 v15, v135
	ds_read_b32 v16, v136
	s_and_saveexec_b64 s[8:9], vcc
	s_xor_b64 s[8:9], exec, s[8:9]
	v_add_u32_e32 v10, 0xffffc000, v18
	v_lshrrev_b32_e32 v10, 6, v10
	v_add_u32_e32 v19, 2, v10
	s_andn2_saveexec_b64 s[8:9], s[8:9]
	v_lshrrev_b32_e32 v11, 19, v11
	v_add_u32_e32 v10, v10, v11
	v_ashrrev_i32_e32 v19, 13, v10
	s_or_b64 exec, exec, s[8:9]
	s_movk_i32 s8, 0x6000
	v_mad_i64_i32 v[10:11], s[8:9], v19, s8, v[68:69]
	v_lshl_add_u64 v[4:5], v[4:5], 2, v[10:11]
	global_load_dword v10, v[4:5], off
	s_waitcnt lgkmcnt(5)
	v_add_f32_e32 v4, 0, v6
	v_add_f32_e32 v7, v4, v7
	s_waitcnt lgkmcnt(4)
	v_add_f32_e32 v2, v7, v2
	v_add_f32_e32 v11, v2, v3
	v_add_u32_e32 v18, v12, v98
	s_waitcnt lgkmcnt(3)
	v_add_f32_e32 v11, v11, v17
	v_add3_u32 v5, v100, v101, s11
	v_or_b32_e32 v6, v99, v18
	s_waitcnt lgkmcnt(2)
	v_add_f32_e32 v11, v11, v14
	v_subrev_u32_e32 v4, 32, v5
	v_ashrrev_i32_e32 v7, 31, v6
	s_waitcnt lgkmcnt(1)
	v_add_f32_e32 v11, v11, v15
	v_ashrrev_i32_e32 v5, 31, v4
	v_lshlrev_b64 v[2:3], 10, v[6:7]
	s_waitcnt lgkmcnt(0)
	v_add_f32_e32 v11, v11, v16
	v_lshl_add_u64 v[8:9], v[8:9], 2, s[2:3]
	v_lshl_add_u64 v[2:3], v[2:3], 0, v[4:5]
	v_cmp_lt_i32_e32 vcc, s62, v6
	s_waitcnt vmcnt(0)
	v_fmac_f32_e32 v13, v11, v10
	global_store_dword v[8:9], v13, off
	v_lshl_add_u64 v[8:9], v[2:3], 2, s[6:7]
	global_load_dword v12, v[8:9], off
	ds_read2st64_b32 v[10:11], v137 offset1:64
	ds_read2st64_b32 v[8:9], v137 offset0:128 offset1:192
	ds_read_b32 v14, v138
	ds_read_b32 v15, v139
	ds_read_b32 v16, v140
	ds_read_b32 v17, v141
	s_and_saveexec_b64 s[6:7], vcc
	s_xor_b64 s[6:7], exec, s[6:7]
	v_add_u32_e32 v6, 0xffffc000, v18
	v_lshrrev_b32_e32 v6, 6, v6
	v_add_u32_e32 v13, 2, v6
	s_andn2_saveexec_b64 s[6:7], s[6:7]
	s_cbranch_execz .LBB0_799
	v_lshrrev_b32_e32 v7, 19, v7
	v_add_u32_e32 v6, v6, v7
	v_ashrrev_i32_e32 v13, 13, v6
	s_branch .LBB0_799
